# down-proj phases (P2 P9 P11 P16) process M-tile groups in reverse order so most recently written ACT/hb tiles are read first
# speedup vs baseline: 1.0114x; 1.0054x over previous
.LBB0_344:
	s_ashr_i32 s4, s7, 3
	s_add_i32 s4, s9, s4
	s_ashr_i32 s5, s4, 31
	s_lshr_b32 s5, s5, 27
	s_add_i32 s5, s4, s5
	s_ashr_i32 s7, s5, 5
	s_andn2_b32 s5, s5, 31
	s_sub_i32 s4, s4, s5
	s_bfe_i32 s5, s4, 0x80000
	s_bfe_u32 s5, s5, 0x3000c
	s_add_i32 s5, s4, s5
	s_bfe_i32 s8, s5, 0x80000
	s_and_b32 s5, s5, 0xf8
	s_sub_i32 s4, s4, s5
	s_lshl_b32 s7, s7, 3
	s_sext_i32_i16 s8, s8
	s_sext_i32_i8 s4, s4
	s_add_i32 s61, s7, s4
	s_xor_b32 s61, s61, 24
	s_ashr_i32 s60, s8, 3

.LBB0_356:
	s_ashr_i32 s4, s22, 3
	s_add_i32 s4, s26, s4
	s_ashr_i32 s5, s4, 31
	s_lshr_b32 s5, s5, 27
	s_add_i32 s5, s4, s5
	s_ashr_i32 s22, s5, 5
	s_lshl_b32 s22, s22, 3
	s_sub_i32 s23, 0x100, s22
	s_min_i32 s23, s23, 8
	s_abs_i32 s26, s23
	v_cvt_f32_u32_e32 v2, s26
	s_sub_i32 s28, 0, s26
	s_andn2_b32 s5, s5, 31
	s_sub_i32 s4, s4, s5
	v_rcp_iflag_f32_e32 v2, v2
	s_abs_i32 s5, s4
	s_xor_b32 s27, s4, s23
	s_ashr_i32 s27, s27, 31
	v_mul_f32_e32 v2, 0x4f7ffffe, v2
	v_cvt_u32_f32_e32 v2, v2
	s_nop 0
	v_readfirstlane_b32 s29, v2
	s_mul_i32 s28, s28, s29
	s_mul_hi_u32 s28, s29, s28
	s_add_i32 s29, s29, s28
	s_mul_hi_u32 s28, s5, s29
	s_mul_i32 s29, s28, s26
	s_sub_i32 s5, s5, s29
	s_add_i32 s33, s28, 1
	s_sub_i32 s29, s5, s26
	s_cmp_ge_u32 s5, s26
	s_cselect_b32 s28, s33, s28
	s_cselect_b32 s5, s29, s5
	s_add_i32 s29, s28, 1
	s_cmp_ge_u32 s5, s26
	s_cselect_b32 s5, s29, s28
	s_xor_b32 s5, s5, s27
	s_sub_i32 s58, s5, s27
	s_mul_i32 s5, s58, s23
	s_sub_i32 s4, s4, s5
	s_add_i32 s59, s22, s4
	s_xor_b32 s59, s59, 24

.LBB0_1159:
	s_ashr_i32 s4, s7, 3
	s_add_i32 s4, s9, s4
	s_ashr_i32 s5, s4, 31
	s_lshr_b32 s5, s5, 27
	s_add_i32 s5, s4, s5
	s_ashr_i32 s7, s5, 5
	s_andn2_b32 s5, s5, 31
	s_sub_i32 s4, s4, s5
	s_bfe_i32 s5, s4, 0x80000
	s_bfe_u32 s5, s5, 0x3000c
	s_add_i32 s5, s4, s5
	s_bfe_i32 s8, s5, 0x80000
	s_and_b32 s5, s5, 0xf8
	s_sub_i32 s4, s4, s5
	s_lshl_b32 s7, s7, 3
	s_sext_i32_i16 s8, s8
	s_sext_i32_i8 s4, s4
	s_add_i32 s47, s7, s4
	s_xor_b32 s47, s47, 24
	s_ashr_i32 s48, s8, 3

.LBB0_1171:
	s_ashr_i32 s4, s18, 3
	s_add_i32 s4, s24, s4
	s_ashr_i32 s5, s4, 31
	s_lshr_b32 s5, s5, 27
	s_add_i32 s5, s4, s5
	s_ashr_i32 s18, s5, 5
	s_lshl_b32 s18, s18, 3
	s_sub_i32 s19, 0x100, s18
	s_min_i32 s19, s19, 8
	s_abs_i32 s24, s19
	v_cvt_f32_u32_e32 v2, s24
	s_sub_i32 s26, 0, s24
	s_andn2_b32 s5, s5, 31
	s_sub_i32 s4, s4, s5
	v_rcp_iflag_f32_e32 v2, v2
	s_abs_i32 s5, s4
	s_xor_b32 s25, s4, s19
	s_ashr_i32 s25, s25, 31
	v_mul_f32_e32 v2, 0x4f7ffffe, v2
	v_cvt_u32_f32_e32 v2, v2
	s_nop 0
	v_readfirstlane_b32 s27, v2
	s_mul_i32 s26, s26, s27
	s_mul_hi_u32 s26, s27, s26
	s_add_i32 s27, s27, s26
	s_mul_hi_u32 s26, s5, s27
	s_mul_i32 s27, s26, s24
	s_sub_i32 s5, s5, s27
	s_add_i32 s33, s26, 1
	s_sub_i32 s27, s5, s24
	s_cmp_ge_u32 s5, s24
	s_cselect_b32 s26, s33, s26
	s_cselect_b32 s5, s27, s5
	s_add_i32 s27, s26, 1
	s_cmp_ge_u32 s5, s24
	s_cselect_b32 s5, s27, s26
	s_xor_b32 s5, s5, s25
	s_sub_i32 s43, s5, s25
	s_mul_i32 s5, s43, s19
	s_sub_i32 s4, s4, s5
	s_add_i32 s46, s18, s4
	s_xor_b32 s46, s46, 24

.LBB0_1444:
	s_ashr_i32 s4, s7, 3
	s_add_i32 s4, s9, s4
	s_ashr_i32 s5, s4, 31
	s_lshr_b32 s5, s5, 27
	s_add_i32 s5, s4, s5
	s_ashr_i32 s7, s5, 5
	s_andn2_b32 s5, s5, 31
	s_sub_i32 s4, s4, s5
	s_bfe_i32 s5, s4, 0x80000
	s_bfe_u32 s5, s5, 0x3000c
	s_add_i32 s5, s4, s5
	s_bfe_i32 s8, s5, 0x80000
	s_and_b32 s5, s5, 0xf8
	s_sub_i32 s4, s4, s5
	s_lshl_b32 s7, s7, 3
	s_sext_i32_i16 s8, s8
	s_sext_i32_i8 s4, s4
	s_add_i32 s53, s7, s4
	s_xor_b32 s53, s53, 24
	s_ashr_i32 s54, s8, 3

.LBB0_1456:
	s_ashr_i32 s4, s20, 3
	s_add_i32 s4, s26, s4
	s_ashr_i32 s5, s4, 31
	s_lshr_b32 s5, s5, 27
	s_add_i32 s5, s4, s5
	s_ashr_i32 s20, s5, 5
	s_lshl_b32 s20, s20, 3
	s_sub_i32 s21, 0x100, s20
	s_min_i32 s21, s21, 8
	s_abs_i32 s26, s21
	v_cvt_f32_u32_e32 v2, s26
	s_sub_i32 s28, 0, s26
	s_andn2_b32 s5, s5, 31
	s_sub_i32 s4, s4, s5
	v_rcp_iflag_f32_e32 v2, v2
	s_abs_i32 s5, s4
	s_xor_b32 s27, s4, s21
	s_ashr_i32 s27, s27, 31
	v_mul_f32_e32 v2, 0x4f7ffffe, v2
	v_cvt_u32_f32_e32 v2, v2
	s_nop 0
	v_readfirstlane_b32 s29, v2
	s_mul_i32 s28, s28, s29
	s_mul_hi_u32 s28, s29, s28
	s_add_i32 s29, s29, s28
	s_mul_hi_u32 s28, s5, s29
	s_mul_i32 s29, s28, s26
	s_sub_i32 s5, s5, s29
	s_add_i32 s33, s28, 1
	s_sub_i32 s29, s5, s26
	s_cmp_ge_u32 s5, s26
	s_cselect_b32 s28, s33, s28
	s_cselect_b32 s5, s29, s5
	s_add_i32 s29, s28, 1
	s_cmp_ge_u32 s5, s26
	s_cselect_b32 s5, s29, s28
	s_xor_b32 s5, s5, s27
	s_sub_i32 s49, s5, s27
	s_mul_i32 s5, s49, s21
	s_sub_i32 s4, s4, s5
	s_add_i32 s52, s20, s4
	s_xor_b32 s52, s52, 24

.LBB0_2021:
	s_add_u32 s21, s50, 0x3d80000
	s_addc_u32 s22, s51, 0
	s_add_i32 s1, s4, s1
	s_ashr_i32 s4, s1, 31
	s_lshr_b32 s4, s4, 27
	v_lshrrev_b32_e32 v1, 1, v180
	s_add_i32 s4, s1, s4
	s_waitcnt vmcnt(0)
	v_and_b32_e32 v8, 24, v1
	v_lshrrev_b32_e32 v1, 5, v180
	s_ashr_i32 s5, s4, 5
	s_and_b32 s4, s4, 0xffe0
	v_and_b32_e32 v1, 4, v1
	v_bfe_u32 v2, v180, 2, 2
	s_sub_i32 s4, s1, s4
	s_waitcnt lgkmcnt(0)
	v_bfe_u32 v7, v180, 2, 4
	v_or3_b32 v1, v1, v2, v8
	v_lshrrev_b32_e32 v2, 3, v180
	s_movk_i32 s3, 0x70
	s_bfe_i32 s1, s4, 0x80000
	v_lshlrev_b32_e32 v6, 4, v180
	v_and_b32_e32 v0, 32, v180
	v_and_or_b32 v3, v2, s3, v7
	s_movk_i32 s3, 0x60
	s_bfe_u32 s1, s1, 0x3000c
	v_bitop3_b32 v4, v6, v0, 48 bitop3:0x6c
	v_and_b32_e32 v5, 64, v180
	v_and_or_b32 v2, v2, s3, v1
	s_add_i32 s6, s4, s1
	v_or_b32_e32 v0, v4, v5
	v_mul_u32_u24_e32 v2, 0x1600, v2
	v_add_u32_e32 v9, 0x2000, v6
	s_bfe_i32 s1, s6, 0x80000
	s_and_b32 s6, s6, 0xf8
	v_or_b32_e32 v130, v2, v0
	v_lshrrev_b32_e32 v2, 7, v9
	s_movk_i32 s3, 0xf0
	s_sub_i32 s4, s4, s6
	v_lshl_or_b32 v128, v3, 7, v0
	v_and_or_b32 v3, v2, s3, v7
	s_movk_i32 s3, 0xe0
	s_lshl_b32 s5, s5, 3
	s_sext_i32_i16 s7, s1
	s_sext_i32_i8 s4, s4
	v_and_or_b32 v1, v2, s3, v1
	s_lshr_b32 s3, s2, 6
	s_add_i32 s38, s5, s4
	s_xor_b32 s38, s38, 24
	s_ashr_i32 s4, s7, 3
	s_lshr_b32 s0, s2, 8
	s_lshl_b32 s23, s3, 10
	s_lshr_b32 s1, s7, 3
	s_mul_hi_i32 s5, s4, 0x160000
	s_mul_i32 s4, s4, 0x160000
	s_add_u32 s12, s21, s4
	s_addc_u32 s13, s22, s5
	s_add_i32 s24, s23, 0
	s_add_i32 m0, s24, 0x10000
	v_mul_u32_u24_e32 v1, 0x1600, v1
	global_load_lds_dwordx4 v130, s[12:13]
	s_add_i32 m0, s24, 0x12000
	v_or_b32_e32 v134, v1, v0
	s_add_u32 s4, s12, 0xb0000
	global_load_lds_dwordx4 v134, s[12:13]
	s_addc_u32 s5, s13, 0
	s_add_i32 m0, s24, 0x14000
	s_mul_i32 s8, s38, 0x160000
	global_load_lds_dwordx4 v130, s[4:5]
	s_add_i32 m0, s24, 0x16000
	s_mul_hi_i32 s6, s38, 0x160000
	s_add_u32 s14, s44, s8
	s_addc_u32 s15, s45, s6
	s_add_i32 s25, s24, 0x2000
	global_load_lds_dwordx4 v134, s[4:5]
	s_mov_b32 m0, s24
	s_add_u32 s4, s14, 0x4000
	v_lshl_or_b32 v132, v3, 7, v0
	global_load_lds_dwordx4 v128, s[14:15]
	s_mov_b32 m0, s25
	s_addc_u32 s5, s15, 0
	s_add_i32 s26, s24, 0x4000
	global_load_lds_dwordx4 v132, s[14:15]
	s_mov_b32 m0, s26
	s_add_i32 s27, s24, 0x6000
	global_load_lds_dwordx4 v128, s[4:5]
	s_mov_b32 m0, s27
	v_mov_b32_e32 v131, 0
	global_load_lds_dwordx4 v132, s[4:5]
	v_mov_b32_e32 v135, v131
	s_cmp_eq_u32 s0, 1
	s_mov_b32 s28, 0
	v_lshl_add_u64 v[2:3], s[12:13], 0, v[130:131]
	v_lshl_add_u64 v[0:1], s[12:13], 0, v[134:135]
	v_mov_b32_e32 v129, v131
	s_cselect_b64 s[4:5], -1, 0
	s_cmp_lg_u32 s0, 1
	v_mov_b32_e32 v133, v131
	s_cbranch_scc1 .LBB0_2023
	s_barrier

.LBB0_2031:
	s_ashr_i32 s0, s10, 3
	s_add_i32 s0, s16, s0
	s_ashr_i32 s1, s0, 31
	s_lshr_b32 s1, s1, 27
	s_add_i32 s1, s0, s1
	s_ashr_i32 s10, s1, 5
	s_lshl_b32 s10, s10, 3
	s_sub_i32 s11, 0x100, s10
	s_min_i32 s11, s11, 8
	s_abs_i32 s16, s11
	v_cvt_f32_u32_e32 v0, s16
	s_sub_i32 s18, 0, s16
	s_andn2_b32 s1, s1, 31
	s_sub_i32 s0, s0, s1
	v_rcp_iflag_f32_e32 v0, v0
	s_abs_i32 s1, s0
	s_xor_b32 s17, s0, s11
	s_ashr_i32 s17, s17, 31
	v_mul_f32_e32 v0, 0x4f7ffffe, v0
	v_cvt_u32_f32_e32 v0, v0
	s_nop 0
	v_readfirstlane_b32 s19, v0
	s_mul_i32 s18, s18, s19
	s_mul_hi_u32 s18, s19, s18
	s_add_i32 s19, s19, s18
	s_mul_hi_u32 s18, s1, s19
	s_mul_i32 s19, s18, s16
	s_sub_i32 s1, s1, s19
	s_add_i32 s33, s18, 1
	s_sub_i32 s19, s1, s16
	s_cmp_ge_u32 s1, s16
	s_cselect_b32 s18, s33, s18
	s_cselect_b32 s1, s19, s1
	s_add_i32 s19, s18, 1
	s_cmp_ge_u32 s1, s16
	s_cselect_b32 s1, s19, s18
	s_xor_b32 s1, s1, s17
	s_sub_i32 s36, s1, s17
	s_mul_i32 s1, s36, s11
	s_sub_i32 s0, s0, s1
	s_add_i32 s37, s10, s0
	s_xor_b32 s37, s37, 24
